# v68 plus P1 epilogue reads the row sum of squares from slot 0 only (P0 stores zeros in the other 15 partial slots), removing the 16-slot reduction
# speedup vs baseline: 1.0036x; 1.0036x over previous
; __device__ __forceinline__ void rows_rstd(const float* ssq, int row0, int fq, float (&rs)[2][4]) {
;     f32x4 p[2][4];
; #pragma unroll
;     for (int ai = 0; ai < 2; ++ai)
; #pragma unroll
;         for (int m = 0; m < 4; ++m) p[ai][m] = *(const f32x4*)(ssq + (size_t)(row0 + ai * HALF + m * 16) * 16 + 4 * fq);
; #pragma unroll
;     for (int ai = 0; ai < 2; ++ai)
; #pragma unroll
;         for (int m = 0; m < 4; ++m) { float s = (p[ai][m][0] + p[ai][m][1]) + (p[ai][m][2] + p[ai][m][3]); s += __shfl_xor(s, 16); s += __shfl_xor(s, 32); rs[ai][m] = __builtin_amdgcn_rsqf(s * (1.0f / (float)DM) + RMS_EPS); }
;     __device__ __forceinline__ void operator()(const f32x4 (&acc)[2][2][4][2], const Unit& u, int wr, int wc, int fr, int fq) const {
;         const int row0 = u.pm * BM + wr * 64 + fr, col0 = u.pn * HALF + wc * 32 + 8 * fq;
;         float rsv[2][4]; rows_rstd(ssq, row0, fq, rsv);
; #pragma unroll
;         for (int ai = 0; ai < 2; ++ai)
; #pragma unroll
;             for (int m = 0; m < 4; ++m) {
;                 const int row = row0 + ai * HALF + m * 16; const float rs = rsv[ai][m], cexp = -1.4426950408889634f * rs, rs2 = rs * rs;
;                 const f32x4 g0 = acc[ai][0][m][0], g1 = acc[ai][0][m][1], u0 = acc[ai][1][m][0], u1 = acc[ai][1][m][1];
;                 const f32x4 t0 = g0 * cexp, t1 = g1 * cexp;
;                 f32x4 d0 = (f32x4){__builtin_amdgcn_exp2f(t0[0]), __builtin_amdgcn_exp2f(t0[1]), __builtin_amdgcn_exp2f(t0[2]), __builtin_amdgcn_exp2f(t0[3])} + 1.0f;
;                 f32x4 d1 = (f32x4){__builtin_amdgcn_exp2f(t1[0]), __builtin_amdgcn_exp2f(t1[1]), __builtin_amdgcn_exp2f(t1[2]), __builtin_amdgcn_exp2f(t1[3])} + 1.0f;
;                 const f32x4 r0 = (f32x4){__builtin_amdgcn_rcpf(d0[0]), __builtin_amdgcn_rcpf(d0[1]), __builtin_amdgcn_rcpf(d0[2]), __builtin_amdgcn_rcpf(d0[3])} * rs2;
;                 const f32x4 r1 = (f32x4){__builtin_amdgcn_rcpf(d1[0]), __builtin_amdgcn_rcpf(d1[1]), __builtin_amdgcn_rcpf(d1[2]), __builtin_amdgcn_rcpf(d1[3])} * rs2;
;                 const f32x4 a0 = (g0 * u0) * r0, a1 = (g1 * u1) * r1;
;                 u32x4 w; w.x = cvt_pk_bf16(a0[0], a0[1]); w.y = cvt_pk_bf16(a0[2], a0[3]); w.z = cvt_pk_bf16(a1[0], a1[1]); w.w = cvt_pk_bf16(a1[2], a1[3]);
;                 *(u32x4*)(O + (((size_t)(row >> 8) * (DFF / BK) + (col0 >> 6)) * BM + (row & 255)) * BK + (col0 & 63)) = w;
.LBB0_136:
	s_lshl_b32 s43, s48, 8
	s_add_i32 s43, s43, s74
	v_or_b32_e32 v152, s43, v154
	v_lshlrev_b32_e32 v162, 6, v152
	v_add_u32_e32 v163, 0x2000, v162
	global_load_dword v164, v162, s[10:11]
	global_load_dword v165, v162, s[10:11] offset:1024
	global_load_dword v166, v162, s[10:11] offset:2048
	global_load_dword v167, v162, s[10:11] offset:3072
	global_load_dword v168, v163, s[10:11]
	global_load_dword v169, v163, s[10:11] offset:1024
	global_load_dword v170, v163, s[10:11] offset:2048
	global_load_dword v171, v163, s[10:11] offset:3072
	v_add_u32_e32 v150, 0x80, v152
	s_lshl_b32 s41, s81, 7
	s_or_b32 s41, s41, s75
	s_ashr_i32 s43, s43, 8
	s_ashr_i32 s41, s41, 6
	s_mul_i32 s43, s43, 44
	s_add_i32 s60, s43, s41
	s_ashr_i32 s61, s60, 31
	v_pk_mul_f32 v[116:117], v[124:125], v[116:117]
	s_lshl_b64 s[60:61], s[60:61], 15
	v_pk_mul_f32 v[114:115], v[122:123], v[114:115]
	v_pk_mul_f32 v[112:113], v[120:121], v[112:113]
	s_add_u32 s60, s36, s60
	v_pk_mul_f32 v[118:119], v[126:127], v[118:119]
	s_addc_u32 s61, s37, s61
	v_pk_mul_f32 v[102:103], v[110:111], v[102:103]
	v_pk_mul_f32 v[100:101], v[108:109], v[100:101]
	v_pk_mul_f32 v[98:99], v[106:107], v[98:99]
	v_pk_mul_f32 v[96:97], v[104:105], v[96:97]
	v_pk_mul_f32 v[84:85], v[92:93], v[84:85]
	v_pk_mul_f32 v[86:87], v[94:95], v[86:87]
	v_pk_mul_f32 v[82:83], v[90:91], v[82:83]
	v_pk_mul_f32 v[80:81], v[88:89], v[80:81]
	v_pk_mul_f32 v[70:71], v[78:79], v[70:71]
	v_pk_mul_f32 v[68:69], v[76:77], v[68:69]
	v_pk_mul_f32 v[66:67], v[74:75], v[66:67]
	v_pk_mul_f32 v[64:65], v[72:73], v[64:65]
	v_pk_mul_f32 v[54:55], v[62:63], v[54:55]
	v_pk_mul_f32 v[52:53], v[60:61], v[52:53]
	v_pk_mul_f32 v[50:51], v[58:59], v[50:51]
	v_pk_mul_f32 v[48:49], v[56:57], v[48:49]
	v_pk_mul_f32 v[38:39], v[46:47], v[38:39]
	v_pk_mul_f32 v[36:37], v[44:45], v[36:37]
	v_pk_mul_f32 v[34:35], v[42:43], v[34:35]
	v_pk_mul_f32 v[32:33], v[40:41], v[32:33]
	v_pk_mul_f32 v[20:21], v[28:29], v[20:21]
	v_pk_mul_f32 v[22:23], v[30:31], v[22:23]
	v_pk_mul_f32 v[18:19], v[26:27], v[18:19]
	v_pk_mul_f32 v[16:17], v[24:25], v[16:17]
	v_pk_mul_f32 v[6:7], v[14:15], v[6:7]
	v_pk_mul_f32 v[4:5], v[12:13], v[4:5]
	v_pk_mul_f32 v[2:3], v[10:11], v[2:3]
	v_pk_mul_f32 v[0:1], v[8:9], v[0:1]
	s_cmp_lg_u64 s[38:39], 0
	s_cbranch_scc0 .Lalign2_skip0
	s_barrier
.Lalign2_skip0:
	s_waitcnt vmcnt(0)
	v_fmamk_f32 v232, v164, 0x3a800000, v160
	v_mov_b32_e32 v233, v232
	v_fmamk_f32 v234, v165, 0x3a800000, v160
	v_mov_b32_e32 v235, v234
	v_fmamk_f32 v238, v166, 0x3a800000, v160
	v_mov_b32_e32 v239, v238
	v_fmamk_f32 v240, v167, 0x3a800000, v160
	v_mov_b32_e32 v241, v240
	v_fmamk_f32 v236, v168, 0x3a800000, v160
	v_mov_b32_e32 v237, v236
	v_fmamk_f32 v242, v169, 0x3a800000, v160
	v_mov_b32_e32 v243, v242
	v_fmamk_f32 v244, v170, 0x3a800000, v160
	v_mov_b32_e32 v245, v244
	v_fmamk_f32 v246, v171, 0x3a800000, v160
	v_mov_b32_e32 v247, v246
	v_rsq_f32_e32 v166, v232
	v_rsq_f32_e32 v172, v234
	v_rsq_f32_e32 v173, v236
	v_rsq_f32_e32 v153, v238
	v_rsq_f32_e32 v161, v240
	v_rsq_f32_e32 v174, v242
	v_rsq_f32_e32 v175, v244
	v_rsq_f32_e32 v151, v246
	v_mul_f32_e32 v136, 0xbfb8aa3b, v166
	v_pk_mul_f32 v[166:167], v[124:125], v[136:137] op_sel_hi:[1,0]
	v_pk_mul_f32 v[164:165], v[126:127], v[136:137] op_sel_hi:[1,0]
	v_pk_mul_f32 v[168:169], v[122:123], v[136:137] op_sel_hi:[1,0]
	v_pk_mul_f32 v[170:171], v[120:121], v[136:137] op_sel_hi:[1,0]
	v_exp_f32_e32 v166, v166
	v_exp_f32_e32 v167, v167
	v_exp_f32_e32 v164, v164
	v_exp_f32_e32 v165, v165
	v_exp_f32_e32 v170, v170
	v_exp_f32_e32 v168, v168
	v_exp_f32_e32 v169, v169
	v_exp_f32_e32 v171, v171
	v_pk_fma_f32 v[166:167], v[166:167], v[232:233], v[232:233]
	v_pk_fma_f32 v[164:165], v[164:165], v[232:233], v[232:233]
	v_pk_fma_f32 v[168:169], v[168:169], v[232:233], v[232:233]
	v_pk_fma_f32 v[170:171], v[170:171], v[232:233], v[232:233]
	v_rcp_f32_e32 v166, v166
	v_rcp_f32_e32 v167, v167
	v_rcp_f32_e32 v164, v164
	v_rcp_f32_e32 v165, v165
	v_rcp_f32_e32 v170, v170
	v_rcp_f32_e32 v171, v171
	v_rcp_f32_e32 v168, v168
	v_rcp_f32_e32 v169, v169
	s_nop 0
	v_pk_mul_f32 v[116:117], v[116:117], v[166:167]
	v_pk_mul_f32 v[120:121], v[114:115], v[168:169]
	v_pk_mul_f32 v[114:115], v[112:113], v[170:171]
	v_cvt_pk_bf16_f32 v112, v116, v117
	v_lshlrev_b32_e32 v116, 7, v152
	v_and_b32_e32 v136, 0x6780, v116
	v_pk_mul_f32 v[118:119], v[118:119], v[164:165]
	v_lshl_add_u64 v[116:117], s[60:61], 0, v[136:137]
	v_mov_b32_e32 v149, v137
	v_cvt_pk_bf16_f32 v113, v118, v119
	v_cvt_pk_bf16_f32 v114, v114, v115
	v_cvt_pk_bf16_f32 v115, v120, v121
	v_lshl_add_u64 v[116:117], v[116:117], 0, v[148:149]
	global_store_dwordx4 v[116:117], v[112:115], off
	s_nop 1
	v_mul_f32_e32 v112, 0xbfb8aa3b, v172
	v_pk_mul_f32 v[118:119], v[110:111], v[112:113] op_sel_hi:[1,0]
	v_pk_mul_f32 v[120:121], v[108:109], v[112:113] op_sel_hi:[1,0]
	v_pk_mul_f32 v[122:123], v[106:107], v[112:113] op_sel_hi:[1,0]
	v_pk_mul_f32 v[112:113], v[104:105], v[112:113] op_sel_hi:[1,0]
	v_exp_f32_e32 v120, v120
	v_exp_f32_e32 v121, v121
	v_exp_f32_e32 v118, v118
	v_exp_f32_e32 v119, v119
	v_exp_f32_e32 v112, v112
	v_exp_f32_e32 v122, v122
	v_exp_f32_e32 v123, v123
	v_exp_f32_e32 v113, v113
	v_pk_fma_f32 v[118:119], v[118:119], v[234:235], v[234:235]
	v_pk_fma_f32 v[120:121], v[120:121], v[234:235], v[234:235]
	v_pk_fma_f32 v[122:123], v[122:123], v[234:235], v[234:235]
	v_pk_fma_f32 v[112:113], v[112:113], v[234:235], v[234:235]
	v_rcp_f32_e32 v120, v120
	v_rcp_f32_e32 v121, v121
	v_rcp_f32_e32 v118, v118
	v_rcp_f32_e32 v119, v119
	v_rcp_f32_e32 v112, v112
	v_rcp_f32_e32 v113, v113
	v_rcp_f32_e32 v122, v122
	v_rcp_f32_e32 v123, v123
	s_nop 0
; __device__ __forceinline__ unsigned cvt_pk_bf16(float lo, float hi) { typedef float f2 __attribute__((ext_vector_type(2))); const bf16v2 r = __builtin_convertvector((f2){lo, hi}, bf16v2); return __builtin_bit_cast(unsigned, r); }
;     __device__ __forceinline__ void operator()(const f32x4 (&acc)[2][2][4][2], const Unit& u, int wr, int wc, int fr, int fq) const {
;     ...
;                 const int row = row0 + ai * HALF + m * 16; const float rs = rsv[ai][m], cexp = -1.4426950408889634f * rs, rs2 = rs * rs;
;                 const f32x4 g0 = acc[ai][0][m][0], g1 = acc[ai][0][m][1], u0 = acc[ai][1][m][0], u1 = acc[ai][1][m][1];
;                 const f32x4 t0 = g0 * cexp, t1 = g1 * cexp;
;                 f32x4 d0 = (f32x4){__builtin_amdgcn_exp2f(t0[0]), __builtin_amdgcn_exp2f(t0[1]), __builtin_amdgcn_exp2f(t0[2]), __builtin_amdgcn_exp2f(t0[3])} + 1.0f;
;                 f32x4 d1 = (f32x4){__builtin_amdgcn_exp2f(t1[0]), __builtin_amdgcn_exp2f(t1[1]), __builtin_amdgcn_exp2f(t1[2]), __builtin_amdgcn_exp2f(t1[3])} + 1.0f;
;                 const f32x4 r0 = (f32x4){__builtin_amdgcn_rcpf(d0[0]), __builtin_amdgcn_rcpf(d0[1]), __builtin_amdgcn_rcpf(d0[2]), __builtin_amdgcn_rcpf(d0[3])} * rs2;
;                 const f32x4 r1 = (f32x4){__builtin_amdgcn_rcpf(d1[0]), __builtin_amdgcn_rcpf(d1[1]), __builtin_amdgcn_rcpf(d1[2]), __builtin_amdgcn_rcpf(d1[3])} * rs2;
;                 const f32x4 a0 = (g0 * u0) * r0, a1 = (g1 * u1) * r1;
;                 u32x4 w; w.x = cvt_pk_bf16(a0[0], a0[1]); w.y = cvt_pk_bf16(a0[2], a0[3]); w.z = cvt_pk_bf16(a1[0], a1[1]); w.w = cvt_pk_bf16(a1[2], a1[3]);
;                 *(u32x4*)(O + (((size_t)(row >> 8) * (DFF / BK) + (col0 >> 6)) * BM + (row & 255)) * BK + (col0 & 63)) = w;
	v_pk_mul_f32 v[102:103], v[102:103], v[118:119]
	v_pk_mul_f32 v[100:101], v[100:101], v[120:121]
	v_pk_mul_f32 v[104:105], v[98:99], v[122:123]
	v_pk_mul_f32 v[98:99], v[96:97], v[112:113]
	v_cvt_pk_bf16_f32 v96, v100, v101
	v_cvt_pk_bf16_f32 v97, v102, v103
	v_cvt_pk_bf16_f32 v98, v98, v99
	v_cvt_pk_bf16_f32 v99, v104, v105
	global_store_dwordx4 v[116:117], v[96:99], off offset:2048
	s_nop 1
	v_mul_f32_e32 v96, 0xbfb8aa3b, v153
	v_pk_mul_f32 v[102:103], v[92:93], v[96:97] op_sel_hi:[1,0]
	v_pk_mul_f32 v[100:101], v[94:95], v[96:97] op_sel_hi:[1,0]
	v_pk_mul_f32 v[104:105], v[90:91], v[96:97] op_sel_hi:[1,0]
	v_pk_mul_f32 v[96:97], v[88:89], v[96:97] op_sel_hi:[1,0]
	v_exp_f32_e32 v102, v102
	v_exp_f32_e32 v103, v103
	v_exp_f32_e32 v100, v100
	v_exp_f32_e32 v101, v101
	v_exp_f32_e32 v96, v96
	v_exp_f32_e32 v104, v104
	v_exp_f32_e32 v105, v105
	v_exp_f32_e32 v97, v97
	v_pk_fma_f32 v[102:103], v[102:103], v[238:239], v[238:239]
	v_pk_fma_f32 v[100:101], v[100:101], v[238:239], v[238:239]
	v_pk_fma_f32 v[104:105], v[104:105], v[238:239], v[238:239]
	v_pk_fma_f32 v[96:97], v[96:97], v[238:239], v[238:239]
	v_rcp_f32_e32 v102, v102
	v_rcp_f32_e32 v103, v103
	v_rcp_f32_e32 v100, v100
	v_rcp_f32_e32 v101, v101
	v_rcp_f32_e32 v96, v96
	v_rcp_f32_e32 v97, v97
	v_rcp_f32_e32 v104, v104
	v_rcp_f32_e32 v105, v105
	s_nop 0
	v_pk_mul_f32 v[84:85], v[84:85], v[102:103]
	v_pk_mul_f32 v[86:87], v[86:87], v[100:101]
	v_pk_mul_f32 v[88:89], v[82:83], v[104:105]
	v_pk_mul_f32 v[82:83], v[80:81], v[96:97]
	v_cvt_pk_bf16_f32 v80, v84, v85
	v_add_co_u32_e32 v84, vcc, s80, v116
	v_cvt_pk_bf16_f32 v81, v86, v87
	v_cvt_pk_bf16_f32 v82, v82, v83
	v_cvt_pk_bf16_f32 v83, v88, v89
	v_addc_co_u32_e32 v85, vcc, 0, v117, vcc
	global_store_dwordx4 v[84:85], v[80:83], off
	s_nop 1
	v_mul_f32_e32 v80, 0xbfb8aa3b, v161
	v_pk_mul_f32 v[86:87], v[78:79], v[80:81] op_sel_hi:[1,0]
	v_pk_mul_f32 v[88:89], v[76:77], v[80:81] op_sel_hi:[1,0]
	v_pk_mul_f32 v[90:91], v[74:75], v[80:81] op_sel_hi:[1,0]
	v_pk_mul_f32 v[80:81], v[72:73], v[80:81] op_sel_hi:[1,0]
	v_exp_f32_e32 v88, v88
	v_exp_f32_e32 v89, v89
	v_exp_f32_e32 v86, v86
	v_exp_f32_e32 v87, v87
	v_exp_f32_e32 v80, v80
	v_exp_f32_e32 v90, v90
	v_exp_f32_e32 v91, v91
	v_exp_f32_e32 v81, v81
	v_pk_fma_f32 v[86:87], v[86:87], v[240:241], v[240:241]
	v_pk_fma_f32 v[88:89], v[88:89], v[240:241], v[240:241]
	v_pk_fma_f32 v[90:91], v[90:91], v[240:241], v[240:241]
	v_pk_fma_f32 v[80:81], v[80:81], v[240:241], v[240:241]
	v_rcp_f32_e32 v88, v88
	v_rcp_f32_e32 v89, v89
	v_rcp_f32_e32 v86, v86
	v_rcp_f32_e32 v87, v87
	v_rcp_f32_e32 v80, v80
	v_rcp_f32_e32 v81, v81
	v_rcp_f32_e32 v90, v90
	v_rcp_f32_e32 v91, v91
	s_nop 0
	v_pk_mul_f32 v[70:71], v[70:71], v[86:87]
	v_pk_mul_f32 v[68:69], v[68:69], v[88:89]
	v_pk_mul_f32 v[72:73], v[66:67], v[90:91]
	v_pk_mul_f32 v[66:67], v[64:65], v[80:81]
	v_cvt_pk_bf16_f32 v64, v68, v69
	v_cvt_pk_bf16_f32 v65, v70, v71
	v_cvt_pk_bf16_f32 v66, v66, v67
	v_cvt_pk_bf16_f32 v67, v72, v73
	global_store_dwordx4 v[84:85], v[64:67], off offset:2048
	s_nop 1
	v_mul_f32_e32 v66, 0xbfb8aa3b, v173
	v_pk_mul_f32 v[70:71], v[62:63], v[66:67] op_sel_hi:[1,0]
	v_pk_mul_f32 v[72:73], v[60:61], v[66:67] op_sel_hi:[1,0]
	v_pk_mul_f32 v[74:75], v[58:59], v[66:67] op_sel_hi:[1,0]
	v_pk_mul_f32 v[66:67], v[56:57], v[66:67] op_sel_hi:[1,0]
	v_exp_f32_e32 v70, v70
	v_exp_f32_e32 v71, v71
	v_exp_f32_e32 v72, v72
	v_exp_f32_e32 v73, v73
	v_exp_f32_e32 v66, v66
	v_exp_f32_e32 v74, v74
	v_exp_f32_e32 v75, v75
	v_exp_f32_e32 v67, v67
	v_pk_fma_f32 v[70:71], v[70:71], v[236:237], v[236:237]
	v_pk_fma_f32 v[72:73], v[72:73], v[236:237], v[236:237]
	v_pk_fma_f32 v[74:75], v[74:75], v[236:237], v[236:237]
	v_pk_fma_f32 v[66:67], v[66:67], v[236:237], v[236:237]
	v_rcp_f32_e32 v70, v70
	v_rcp_f32_e32 v71, v71
	v_rcp_f32_e32 v72, v72
	v_rcp_f32_e32 v73, v73
	v_rcp_f32_e32 v66, v66
	v_rcp_f32_e32 v67, v67
	v_rcp_f32_e32 v74, v74
	v_rcp_f32_e32 v75, v75
	v_lshrrev_b32_e32 v64, 8, v150
	v_mad_i32_i24 v64, v64, 44, s41
	v_ashrrev_i32_e32 v65, 31, v64
	s_nop 0
	v_pk_mul_f32 v[54:55], v[54:55], v[70:71]
	v_lshlrev_b64 v[64:65], 15, v[64:65]
	v_pk_mul_f32 v[52:53], v[52:53], v[72:73]
	v_pk_mul_f32 v[56:57], v[50:51], v[74:75]
	v_pk_mul_f32 v[50:51], v[48:49], v[66:67]
	v_cvt_pk_bf16_f32 v49, v54, v55
	v_lshlrev_b32_e32 v54, 7, v150
; #define PG8_BAR __builtin_amdgcn_s_barrier()
;     __device__ __forceinline__ void operator()(const f32x4 (&acc)[2][2][4][2], const Unit& u, int wr, int wc, int fr, int fq) const {
;     ...
;                 const int row = row0 + ai * HALF + m * 16; const float rs = rsv[ai][m], cexp = -1.4426950408889634f * rs, rs2 = rs * rs;
;                 const f32x4 g0 = acc[ai][0][m][0], g1 = acc[ai][0][m][1], u0 = acc[ai][1][m][0], u1 = acc[ai][1][m][1];
;                 const f32x4 t0 = g0 * cexp, t1 = g1 * cexp;
;                 f32x4 d0 = (f32x4){__builtin_amdgcn_exp2f(t0[0]), __builtin_amdgcn_exp2f(t0[1]), __builtin_amdgcn_exp2f(t0[2]), __builtin_amdgcn_exp2f(t0[3])} + 1.0f;
;                 f32x4 d1 = (f32x4){__builtin_amdgcn_exp2f(t1[0]), __builtin_amdgcn_exp2f(t1[1]), __builtin_amdgcn_exp2f(t1[2]), __builtin_amdgcn_exp2f(t1[3])} + 1.0f;
;                 const f32x4 r0 = (f32x4){__builtin_amdgcn_rcpf(d0[0]), __builtin_amdgcn_rcpf(d0[1]), __builtin_amdgcn_rcpf(d0[2]), __builtin_amdgcn_rcpf(d0[3])} * rs2;
;                 const f32x4 r1 = (f32x4){__builtin_amdgcn_rcpf(d1[0]), __builtin_amdgcn_rcpf(d1[1]), __builtin_amdgcn_rcpf(d1[2]), __builtin_amdgcn_rcpf(d1[3])} * rs2;
;                 const f32x4 a0 = (g0 * u0) * r0, a1 = (g1 * u1) * r1;
;                 u32x4 w; w.x = cvt_pk_bf16(a0[0], a0[1]); w.y = cvt_pk_bf16(a0[2], a0[3]); w.z = cvt_pk_bf16(a1[0], a1[1]); w.w = cvt_pk_bf16(a1[2], a1[3]);
;                 *(u32x4*)(O + (((size_t)(row >> 8) * (DFF / BK) + (col0 >> 6)) * BM + (row & 255)) * BK + (col0 & 63)) = w;
; template <class Epi, class Sched, bool ALIGN_EPI = false, bool SP2 = false, bool ATILED = false>
; __device__ __forceinline__ void gemm_phase(PG8_LAS unsigned char* lds, const Gemm g, const Sched& S, const Epi& E) {
;     ...
;         if constexpr (!Epi::AFTER_DRAIN) { E(acc, cur, wr, wc, fr, fq); S.done(cur); }
;         if (!has_next) break;
; #pragma unroll
;         for (int a = 0; a < 2; ++a)
; #pragma unroll
;             for (int b = 0; b < 2; ++b)
; #pragma unroll
;                 for (int m = 0; m < 4; ++m)
; #pragma unroll
;                     for (int n = 0; n < 2; ++n) acc[a][b][m][n] = (f32x4){0.f, 0.f, 0.f, 0.f};
;         cur = nxt; cA = nA; cB = nB; ++ui;
;         if constexpr (ALIGN_EPI) { if (wr == 1) PG8_BAR; }
	v_cvt_pk_bf16_f32 v48, v52, v53
	v_lshl_add_u64 v[52:53], s[36:37], 0, v[64:65]
	v_and_b32_e32 v136, 0x6780, v54
	v_lshl_add_u64 v[52:53], v[52:53], 0, v[136:137]
	v_cvt_pk_bf16_f32 v50, v50, v51
	v_cvt_pk_bf16_f32 v51, v56, v57
	v_lshl_add_u64 v[52:53], v[52:53], 0, v[148:149]
	global_store_dwordx4 v[52:53], v[48:51], off
	s_nop 1
	v_mul_f32_e32 v48, 0xbfb8aa3b, v174
	v_pk_mul_f32 v[54:55], v[46:47], v[48:49] op_sel_hi:[1,0]
	v_pk_mul_f32 v[56:57], v[44:45], v[48:49] op_sel_hi:[1,0]
	v_pk_mul_f32 v[58:59], v[42:43], v[48:49] op_sel_hi:[1,0]
	v_pk_mul_f32 v[48:49], v[40:41], v[48:49] op_sel_hi:[1,0]
	v_exp_f32_e32 v56, v56
	v_exp_f32_e32 v57, v57
	v_exp_f32_e32 v54, v54
	v_exp_f32_e32 v55, v55
	v_exp_f32_e32 v48, v48
	v_exp_f32_e32 v58, v58
	v_exp_f32_e32 v59, v59
	v_exp_f32_e32 v49, v49
	v_pk_fma_f32 v[54:55], v[54:55], v[242:243], v[242:243]
	v_pk_fma_f32 v[56:57], v[56:57], v[242:243], v[242:243]
	v_pk_fma_f32 v[58:59], v[58:59], v[242:243], v[242:243]
	v_pk_fma_f32 v[48:49], v[48:49], v[242:243], v[242:243]
	v_rcp_f32_e32 v56, v56
	v_rcp_f32_e32 v57, v57
	v_rcp_f32_e32 v54, v54
	v_rcp_f32_e32 v55, v55
	v_rcp_f32_e32 v48, v48
	v_rcp_f32_e32 v49, v49
	v_rcp_f32_e32 v58, v58
	v_rcp_f32_e32 v59, v59
	s_nop 0
	v_pk_mul_f32 v[38:39], v[38:39], v[54:55]
	v_pk_mul_f32 v[36:37], v[36:37], v[56:57]
	v_pk_mul_f32 v[40:41], v[34:35], v[58:59]
	v_pk_mul_f32 v[34:35], v[32:33], v[48:49]
	v_cvt_pk_bf16_f32 v32, v36, v37
	v_cvt_pk_bf16_f32 v33, v38, v39
	v_cvt_pk_bf16_f32 v34, v34, v35
	v_cvt_pk_bf16_f32 v35, v40, v41
	global_store_dwordx4 v[52:53], v[32:35], off offset:2048
	s_nop 1
	v_mul_f32_e32 v32, 0xbfb8aa3b, v175
	v_pk_mul_f32 v[38:39], v[28:29], v[32:33] op_sel_hi:[1,0]
	v_pk_mul_f32 v[36:37], v[30:31], v[32:33] op_sel_hi:[1,0]
	v_pk_mul_f32 v[40:41], v[26:27], v[32:33] op_sel_hi:[1,0]
	v_pk_mul_f32 v[32:33], v[24:25], v[32:33] op_sel_hi:[1,0]
	v_exp_f32_e32 v38, v38
	v_exp_f32_e32 v39, v39
	v_exp_f32_e32 v36, v36
	v_exp_f32_e32 v37, v37
	v_exp_f32_e32 v32, v32
	v_exp_f32_e32 v40, v40
	v_exp_f32_e32 v41, v41
	v_exp_f32_e32 v33, v33
	v_pk_fma_f32 v[38:39], v[38:39], v[244:245], v[244:245]
	v_pk_fma_f32 v[36:37], v[36:37], v[244:245], v[244:245]
	v_pk_fma_f32 v[40:41], v[40:41], v[244:245], v[244:245]
	v_pk_fma_f32 v[32:33], v[32:33], v[244:245], v[244:245]
	v_rcp_f32_e32 v38, v38
	v_rcp_f32_e32 v39, v39
	v_rcp_f32_e32 v36, v36
	v_rcp_f32_e32 v37, v37
	v_rcp_f32_e32 v32, v32
	v_rcp_f32_e32 v33, v33
	v_rcp_f32_e32 v40, v40
	v_rcp_f32_e32 v41, v41
	s_nop 0
	v_pk_mul_f32 v[20:21], v[20:21], v[38:39]
	v_pk_mul_f32 v[22:23], v[22:23], v[36:37]
	v_pk_mul_f32 v[24:25], v[18:19], v[40:41]
	v_pk_mul_f32 v[18:19], v[16:17], v[32:33]
	v_cvt_pk_bf16_f32 v16, v20, v21
	v_add_co_u32_e32 v20, vcc, s80, v52
	v_cvt_pk_bf16_f32 v17, v22, v23
	v_cvt_pk_bf16_f32 v18, v18, v19
	v_cvt_pk_bf16_f32 v19, v24, v25
	v_addc_co_u32_e32 v21, vcc, 0, v53, vcc
	global_store_dwordx4 v[20:21], v[16:19], off
	s_andn2_b64 vcc, exec, s[0:1]
	s_mov_b64 s[0:1], -1
	v_mul_f32_e32 v16, 0xbfb8aa3b, v151
	v_pk_mul_f32 v[22:23], v[14:15], v[16:17] op_sel_hi:[1,0]
	v_pk_mul_f32 v[24:25], v[12:13], v[16:17] op_sel_hi:[1,0]
	v_pk_mul_f32 v[26:27], v[10:11], v[16:17] op_sel_hi:[1,0]
	v_pk_mul_f32 v[16:17], v[8:9], v[16:17] op_sel_hi:[1,0]
	v_exp_f32_e32 v24, v24
	v_exp_f32_e32 v25, v25
	v_exp_f32_e32 v22, v22
	v_exp_f32_e32 v23, v23
	v_exp_f32_e32 v16, v16
	v_exp_f32_e32 v26, v26
	v_exp_f32_e32 v27, v27
	v_exp_f32_e32 v17, v17
	v_pk_fma_f32 v[22:23], v[22:23], v[246:247], v[246:247]
	v_pk_fma_f32 v[24:25], v[24:25], v[246:247], v[246:247]
	v_pk_fma_f32 v[26:27], v[26:27], v[246:247], v[246:247]
	v_pk_fma_f32 v[16:17], v[16:17], v[246:247], v[246:247]
	v_rcp_f32_e32 v24, v24
	v_rcp_f32_e32 v25, v25
	v_rcp_f32_e32 v22, v22
	v_rcp_f32_e32 v23, v23
	v_rcp_f32_e32 v16, v16
	v_rcp_f32_e32 v17, v17
	v_rcp_f32_e32 v26, v26
	v_rcp_f32_e32 v27, v27
	s_nop 0
	v_pk_mul_f32 v[6:7], v[6:7], v[22:23]
	v_pk_mul_f32 v[4:5], v[4:5], v[24:25]
	v_pk_mul_f32 v[8:9], v[2:3], v[26:27]
	v_pk_mul_f32 v[2:3], v[0:1], v[16:17]
	v_cvt_pk_bf16_f32 v0, v4, v5
	v_cvt_pk_bf16_f32 v1, v6, v7
	v_cvt_pk_bf16_f32 v2, v2, v3
	v_cvt_pk_bf16_f32 v3, v8, v9
	global_store_dwordx4 v[20:21], v[0:3], off offset:2048
	s_cbranch_vccnz .LBB0_129
	s_andn2_b64 vcc, exec, s[4:5]
	s_cbranch_vccnz .LBB0_128
	s_barrier
	s_branch .LBB0_128

; __device__ __forceinline__ void rows_rstd(const float* ssq, int row0, int fq, float (&rs)[2][4]) {
;     f32x4 p[2][4];
; #pragma unroll
;     for (int ai = 0; ai < 2; ++ai)
; #pragma unroll
;         for (int m = 0; m < 4; ++m) p[ai][m] = *(const f32x4*)(ssq + (size_t)(row0 + ai * HALF + m * 16) * 16 + 4 * fq);
; #pragma unroll
;     for (int ai = 0; ai < 2; ++ai)
; #pragma unroll
;         for (int m = 0; m < 4; ++m) { float s = (p[ai][m][0] + p[ai][m][1]) + (p[ai][m][2] + p[ai][m][3]); s += __shfl_xor(s, 16); s += __shfl_xor(s, 32); rs[ai][m] = __builtin_amdgcn_rsqf(s * (1.0f / (float)DM) + RMS_EPS); }
;     __device__ __forceinline__ void operator()(const f32x4 (&acc)[2][2][4][2], const Unit& u, int wr, int wc, int fr, int fq) const {
;         const int row0 = u.pm * BM + wr * 64 + fr, col0 = u.pn * HALF + wc * 32 + 8 * fq;
;         float rsv[2][4]; rows_rstd(ssq, row0, fq, rsv);
; #pragma unroll
;         for (int ai = 0; ai < 2; ++ai)
; #pragma unroll
;             for (int m = 0; m < 4; ++m) {
;                 const int row = row0 + ai * HALF + m * 16; const float rs = rsv[ai][m], cexp = -1.4426950408889634f * rs, rs2 = rs * rs;
;                 const f32x4 g0 = acc[ai][0][m][0], g1 = acc[ai][0][m][1], u0 = acc[ai][1][m][0], u1 = acc[ai][1][m][1];
;                 const f32x4 t0 = g0 * cexp, t1 = g1 * cexp;
;                 f32x4 d0 = (f32x4){__builtin_amdgcn_exp2f(t0[0]), __builtin_amdgcn_exp2f(t0[1]), __builtin_amdgcn_exp2f(t0[2]), __builtin_amdgcn_exp2f(t0[3])} + 1.0f;
;                 f32x4 d1 = (f32x4){__builtin_amdgcn_exp2f(t1[0]), __builtin_amdgcn_exp2f(t1[1]), __builtin_amdgcn_exp2f(t1[2]), __builtin_amdgcn_exp2f(t1[3])} + 1.0f;
;                 const f32x4 r0 = (f32x4){__builtin_amdgcn_rcpf(d0[0]), __builtin_amdgcn_rcpf(d0[1]), __builtin_amdgcn_rcpf(d0[2]), __builtin_amdgcn_rcpf(d0[3])} * rs2;
;                 const f32x4 r1 = (f32x4){__builtin_amdgcn_rcpf(d1[0]), __builtin_amdgcn_rcpf(d1[1]), __builtin_amdgcn_rcpf(d1[2]), __builtin_amdgcn_rcpf(d1[3])} * rs2;
;                 const f32x4 a0 = (g0 * u0) * r0, a1 = (g1 * u1) * r1;
;                 u32x4 w; w.x = cvt_pk_bf16(a0[0], a0[1]); w.y = cvt_pk_bf16(a0[2], a0[3]); w.z = cvt_pk_bf16(a1[0], a1[1]); w.w = cvt_pk_bf16(a1[2], a1[3]);
;                 *(u32x4*)(O + (((size_t)(row >> 8) * (DFF / BK) + (col0 >> 6)) * BM + (row & 255)) * BK + (col0 & 63)) = w;
.Lalign2_skip4:
	s_waitcnt vmcnt(0)
	v_mov_b32_e32 v194, v163
	v_mov_b32_e32 v195, v164
	v_mov_b32_e32 v163, v165
	v_pk_add_f32 v[162:163], v[194:195], v[162:163]
	v_mov_b32_e32 v164, v167
	v_mov_b32_e32 v165, v168
	v_mov_b32_e32 v167, v169
	v_add_f32_e32 v151, v162, v163
	v_pk_add_f32 v[162:163], v[164:165], v[166:167]
	v_mov_b32_e32 v168, v171
	v_mov_b32_e32 v169, v172
	v_mov_b32_e32 v171, v173
	v_mov_b32_e32 v172, v175
	v_mov_b32_e32 v173, v176
	v_mov_b32_e32 v175, v177
	v_mov_b32_e32 v176, v179
	v_mov_b32_e32 v177, v180
	v_mov_b32_e32 v179, v181
	v_pk_add_f32 v[164:165], v[168:169], v[170:171]
	v_pk_add_f32 v[166:167], v[172:173], v[174:175]
	ds_bpermute_b32 v153, v136, v151
	v_add_f32_e32 v161, v162, v163
	v_pk_add_f32 v[168:169], v[176:177], v[178:179]
	v_add_f32_e32 v162, v164, v165
	v_add_f32_e32 v163, v166, v167
	ds_bpermute_b32 v166, v136, v161
	v_add_f32_e32 v164, v168, v169
	ds_bpermute_b32 v167, v136, v162
	ds_bpermute_b32 v168, v136, v163
	ds_bpermute_b32 v169, v136, v164
	s_waitcnt lgkmcnt(4)
	v_add_f32_e32 v151, v151, v153
	ds_bpermute_b32 v153, v149, v151
	s_waitcnt lgkmcnt(4)
	v_add_f32_e32 v161, v161, v166
	s_waitcnt lgkmcnt(3)
	v_add_f32_e32 v162, v162, v167
	s_waitcnt lgkmcnt(2)
	v_add_f32_e32 v163, v163, v168
	ds_bpermute_b32 v166, v149, v161
	v_mov_b32_e32 v180, v183
	v_mov_b32_e32 v181, v184
	v_mov_b32_e32 v183, v185
	s_waitcnt lgkmcnt(2)
	v_add_f32_e32 v164, v164, v169
	ds_bpermute_b32 v167, v149, v162
	ds_bpermute_b32 v168, v149, v163
	v_pk_add_f32 v[170:171], v[180:181], v[182:183]
	ds_bpermute_b32 v169, v149, v164
	v_add_f32_e32 v165, v170, v171
	ds_bpermute_b32 v170, v136, v165
	s_waitcnt lgkmcnt(5)
	v_add_f32_e32 v151, v151, v153
	v_fmamk_f32 v232, v151, 0x3a800000, v160
	v_mov_b32_e32 v233, v232
	s_waitcnt lgkmcnt(4)
	v_add_f32_e32 v153, v161, v166
	s_waitcnt lgkmcnt(3)
	v_add_f32_e32 v161, v162, v167
	s_waitcnt lgkmcnt(2)
	v_add_f32_e32 v162, v163, v168
	v_rsq_f32_e32 v166, v232
	v_fmamk_f32 v234, v153, 0x3a800000, v160
	v_mov_b32_e32 v235, v234
	v_fmamk_f32 v238, v161, 0x3a800000, v160
	v_mov_b32_e32 v239, v238
	v_fmamk_f32 v240, v162, 0x3a800000, v160
	v_mov_b32_e32 v241, v240
	v_rsq_f32_e32 v172, v234
	s_waitcnt lgkmcnt(1)
	v_add_f32_e32 v151, v164, v169
	v_mov_b32_e32 v162, v187
	v_mov_b32_e32 v163, v188
	v_mov_b32_e32 v187, v189
	v_fmamk_f32 v236, v151, 0x3a800000, v160
	v_mov_b32_e32 v237, v236
	v_pk_add_f32 v[162:163], v[162:163], v[186:187]
	v_rsq_f32_e32 v173, v236
	s_waitcnt lgkmcnt(0)
	v_add_f32_e32 v151, v165, v170
	v_add_f32_e32 v165, v162, v163
	v_mov_b32_e32 v162, v191
	v_mov_b32_e32 v163, v192
	v_mov_b32_e32 v191, v193
	v_pk_add_f32 v[162:163], v[162:163], v[190:191]
	ds_bpermute_b32 v167, v136, v165
	v_add_f32_e32 v162, v162, v163
	ds_bpermute_b32 v136, v136, v162
	ds_bpermute_b32 v164, v149, v151
	v_rsq_f32_e32 v153, v238
	s_waitcnt lgkmcnt(2)
	v_add_f32_e32 v163, v165, v167
	v_rsq_f32_e32 v161, v240
	s_waitcnt lgkmcnt(1)
	v_add_f32_e32 v136, v162, v136
	s_waitcnt lgkmcnt(0)
	v_add_f32_e32 v151, v151, v164
	ds_bpermute_b32 v164, v149, v163
	ds_bpermute_b32 v149, v149, v136
	v_fmamk_f32 v242, v151, 0x3a800000, v160
	v_mov_b32_e32 v243, v242
	v_rsq_f32_e32 v174, v242
	s_waitcnt lgkmcnt(1)
	v_add_f32_e32 v151, v163, v164
	s_waitcnt lgkmcnt(0)
	v_add_f32_e32 v136, v136, v149
	v_fmamk_f32 v244, v151, 0x3a800000, v160
	v_mov_b32_e32 v245, v244
	v_fmamk_f32 v246, v136, 0x3a800000, v160
	v_mov_b32_e32 v247, v246
	v_rsq_f32_e32 v175, v244
	v_rsq_f32_e32 v151, v246
	v_mul_f32_e32 v136, 0xbfb8aa3b, v166
	v_pk_mul_f32 v[166:167], v[124:125], v[136:137] op_sel_hi:[1,0]
	v_pk_mul_f32 v[164:165], v[126:127], v[136:137] op_sel_hi:[1,0]
	v_pk_mul_f32 v[168:169], v[122:123], v[136:137] op_sel_hi:[1,0]
	v_pk_mul_f32 v[170:171], v[120:121], v[136:137] op_sel_hi:[1,0]
	v_exp_f32_e32 v166, v166
	v_exp_f32_e32 v167, v167
	v_exp_f32_e32 v164, v164
	v_exp_f32_e32 v165, v165
	v_exp_f32_e32 v170, v170
	v_exp_f32_e32 v168, v168
	v_exp_f32_e32 v169, v169
	v_exp_f32_e32 v171, v171
	v_pk_fma_f32 v[166:167], v[166:167], v[232:233], v[232:233]
	v_pk_fma_f32 v[164:165], v[164:165], v[232:233], v[232:233]
	v_pk_fma_f32 v[168:169], v[168:169], v[232:233], v[232:233]
	v_pk_fma_f32 v[170:171], v[170:171], v[232:233], v[232:233]
	v_rcp_f32_e32 v166, v166
	v_rcp_f32_e32 v167, v167
	v_rcp_f32_e32 v164, v164
	v_rcp_f32_e32 v165, v165
	v_rcp_f32_e32 v170, v170
	v_rcp_f32_e32 v171, v171
	v_rcp_f32_e32 v168, v168
	v_rcp_f32_e32 v169, v169
	s_nop 0
	v_pk_mul_f32 v[116:117], v[116:117], v[166:167]
	v_pk_mul_f32 v[120:121], v[114:115], v[168:169]
	v_pk_mul_f32 v[114:115], v[112:113], v[170:171]
	v_cvt_pk_bf16_f32 v112, v116, v117
	v_lshlrev_b32_e32 v116, 7, v152
	v_and_b32_e32 v136, 0x6780, v116
	v_pk_mul_f32 v[118:119], v[118:119], v[164:165]
	v_lshl_add_u64 v[116:117], s[20:21], 0, v[136:137]
	v_mov_b32_e32 v149, v137
	v_cvt_pk_bf16_f32 v113, v118, v119
	v_cvt_pk_bf16_f32 v114, v114, v115
	v_cvt_pk_bf16_f32 v115, v120, v121
	v_lshl_add_u64 v[116:117], v[116:117], 0, v[148:149]
	global_store_dwordx4 v[116:117], v[112:115], off
	s_nop 1
	v_mul_f32_e32 v112, 0xbfb8aa3b, v172
	v_pk_mul_f32 v[118:119], v[110:111], v[112:113] op_sel_hi:[1,0]
	v_pk_mul_f32 v[120:121], v[108:109], v[112:113] op_sel_hi:[1,0]
	v_pk_mul_f32 v[122:123], v[106:107], v[112:113] op_sel_hi:[1,0]
	v_pk_mul_f32 v[112:113], v[104:105], v[112:113] op_sel_hi:[1,0]
	v_exp_f32_e32 v120, v120
	v_exp_f32_e32 v121, v121
	v_exp_f32_e32 v118, v118
	v_exp_f32_e32 v119, v119
	v_exp_f32_e32 v112, v112
	v_exp_f32_e32 v122, v122
	v_exp_f32_e32 v123, v123
	v_exp_f32_e32 v113, v113
	v_pk_fma_f32 v[118:119], v[118:119], v[234:235], v[234:235]
	v_pk_fma_f32 v[120:121], v[120:121], v[234:235], v[234:235]
; __device__ __forceinline__ unsigned cvt_pk_bf16(float lo, float hi) { typedef float f2 __attribute__((ext_vector_type(2))); const bf16v2 r = __builtin_convertvector((f2){lo, hi}, bf16v2); return __builtin_bit_cast(unsigned, r); }
;     __device__ __forceinline__ void operator()(const f32x4 (&acc)[2][2][4][2], const Unit& u, int wr, int wc, int fr, int fq) const {
;     ...
;                 const int row = row0 + ai * HALF + m * 16; const float rs = rsv[ai][m], cexp = -1.4426950408889634f * rs, rs2 = rs * rs;
;                 const f32x4 g0 = acc[ai][0][m][0], g1 = acc[ai][0][m][1], u0 = acc[ai][1][m][0], u1 = acc[ai][1][m][1];
;                 const f32x4 t0 = g0 * cexp, t1 = g1 * cexp;
;                 f32x4 d0 = (f32x4){__builtin_amdgcn_exp2f(t0[0]), __builtin_amdgcn_exp2f(t0[1]), __builtin_amdgcn_exp2f(t0[2]), __builtin_amdgcn_exp2f(t0[3])} + 1.0f;
;                 f32x4 d1 = (f32x4){__builtin_amdgcn_exp2f(t1[0]), __builtin_amdgcn_exp2f(t1[1]), __builtin_amdgcn_exp2f(t1[2]), __builtin_amdgcn_exp2f(t1[3])} + 1.0f;
;                 const f32x4 r0 = (f32x4){__builtin_amdgcn_rcpf(d0[0]), __builtin_amdgcn_rcpf(d0[1]), __builtin_amdgcn_rcpf(d0[2]), __builtin_amdgcn_rcpf(d0[3])} * rs2;
;                 const f32x4 r1 = (f32x4){__builtin_amdgcn_rcpf(d1[0]), __builtin_amdgcn_rcpf(d1[1]), __builtin_amdgcn_rcpf(d1[2]), __builtin_amdgcn_rcpf(d1[3])} * rs2;
;                 const f32x4 a0 = (g0 * u0) * r0, a1 = (g1 * u1) * r1;
;                 u32x4 w; w.x = cvt_pk_bf16(a0[0], a0[1]); w.y = cvt_pk_bf16(a0[2], a0[3]); w.z = cvt_pk_bf16(a1[0], a1[1]); w.w = cvt_pk_bf16(a1[2], a1[3]);
;                 *(u32x4*)(O + (((size_t)(row >> 8) * (DFF / BK) + (col0 >> 6)) * BM + (row & 255)) * BK + (col0 & 63)) = w;
	v_pk_fma_f32 v[122:123], v[122:123], v[234:235], v[234:235]
	v_pk_fma_f32 v[112:113], v[112:113], v[234:235], v[234:235]
	v_rcp_f32_e32 v120, v120
	v_rcp_f32_e32 v121, v121
	v_rcp_f32_e32 v118, v118
	v_rcp_f32_e32 v119, v119
	v_rcp_f32_e32 v112, v112
	v_rcp_f32_e32 v113, v113
	v_rcp_f32_e32 v122, v122
	v_rcp_f32_e32 v123, v123
	s_nop 0
	v_pk_mul_f32 v[102:103], v[102:103], v[118:119]
	v_pk_mul_f32 v[100:101], v[100:101], v[120:121]
	v_pk_mul_f32 v[104:105], v[98:99], v[122:123]
	v_pk_mul_f32 v[98:99], v[96:97], v[112:113]
	v_cvt_pk_bf16_f32 v96, v100, v101
	v_cvt_pk_bf16_f32 v97, v102, v103
	v_cvt_pk_bf16_f32 v98, v98, v99
	v_cvt_pk_bf16_f32 v99, v104, v105
	global_store_dwordx4 v[116:117], v[96:99], off offset:2048
	s_nop 1
	v_mul_f32_e32 v96, 0xbfb8aa3b, v153
	v_pk_mul_f32 v[102:103], v[92:93], v[96:97] op_sel_hi:[1,0]
	v_pk_mul_f32 v[100:101], v[94:95], v[96:97] op_sel_hi:[1,0]
	v_pk_mul_f32 v[104:105], v[90:91], v[96:97] op_sel_hi:[1,0]
	v_pk_mul_f32 v[96:97], v[88:89], v[96:97] op_sel_hi:[1,0]
	v_exp_f32_e32 v102, v102
	v_exp_f32_e32 v103, v103
	v_exp_f32_e32 v100, v100
	v_exp_f32_e32 v101, v101
	v_exp_f32_e32 v96, v96
	v_exp_f32_e32 v104, v104
	v_exp_f32_e32 v105, v105
	v_exp_f32_e32 v97, v97
	v_pk_fma_f32 v[102:103], v[102:103], v[238:239], v[238:239]
	v_pk_fma_f32 v[100:101], v[100:101], v[238:239], v[238:239]
	v_pk_fma_f32 v[104:105], v[104:105], v[238:239], v[238:239]
	v_pk_fma_f32 v[96:97], v[96:97], v[238:239], v[238:239]
	v_rcp_f32_e32 v102, v102
	v_rcp_f32_e32 v103, v103
	v_rcp_f32_e32 v100, v100
	v_rcp_f32_e32 v101, v101
	v_rcp_f32_e32 v96, v96
	v_rcp_f32_e32 v97, v97
	v_rcp_f32_e32 v104, v104
	v_rcp_f32_e32 v105, v105
	s_nop 0
	v_pk_mul_f32 v[84:85], v[84:85], v[102:103]
	v_pk_mul_f32 v[86:87], v[86:87], v[100:101]
	v_pk_mul_f32 v[88:89], v[82:83], v[104:105]
	v_pk_mul_f32 v[82:83], v[80:81], v[96:97]
	v_cvt_pk_bf16_f32 v80, v84, v85
	v_add_co_u32_e32 v84, vcc, s62, v116
	v_cvt_pk_bf16_f32 v81, v86, v87
	v_cvt_pk_bf16_f32 v82, v82, v83
	v_cvt_pk_bf16_f32 v83, v88, v89
	v_addc_co_u32_e32 v85, vcc, 0, v117, vcc
	global_store_dwordx4 v[84:85], v[80:83], off
	s_nop 1
	v_mul_f32_e32 v80, 0xbfb8aa3b, v161
	v_pk_mul_f32 v[86:87], v[78:79], v[80:81] op_sel_hi:[1,0]
	v_pk_mul_f32 v[88:89], v[76:77], v[80:81] op_sel_hi:[1,0]
	v_pk_mul_f32 v[90:91], v[74:75], v[80:81] op_sel_hi:[1,0]
	v_pk_mul_f32 v[80:81], v[72:73], v[80:81] op_sel_hi:[1,0]
	v_exp_f32_e32 v88, v88
	v_exp_f32_e32 v89, v89
	v_exp_f32_e32 v86, v86
	v_exp_f32_e32 v87, v87
	v_exp_f32_e32 v80, v80
	v_exp_f32_e32 v90, v90
	v_exp_f32_e32 v91, v91
	v_exp_f32_e32 v81, v81
	v_pk_fma_f32 v[86:87], v[86:87], v[240:241], v[240:241]
	v_pk_fma_f32 v[88:89], v[88:89], v[240:241], v[240:241]
	v_pk_fma_f32 v[90:91], v[90:91], v[240:241], v[240:241]
	v_pk_fma_f32 v[80:81], v[80:81], v[240:241], v[240:241]
	v_rcp_f32_e32 v88, v88
	v_rcp_f32_e32 v89, v89
	v_rcp_f32_e32 v86, v86
	v_rcp_f32_e32 v87, v87
	v_rcp_f32_e32 v80, v80
	v_rcp_f32_e32 v81, v81
	v_rcp_f32_e32 v90, v90
	v_rcp_f32_e32 v91, v91
	s_nop 0
	v_pk_mul_f32 v[70:71], v[70:71], v[86:87]
	v_pk_mul_f32 v[68:69], v[68:69], v[88:89]
	v_pk_mul_f32 v[72:73], v[66:67], v[90:91]
	v_pk_mul_f32 v[66:67], v[64:65], v[80:81]
	v_cvt_pk_bf16_f32 v64, v68, v69
	v_cvt_pk_bf16_f32 v65, v70, v71
	v_cvt_pk_bf16_f32 v66, v66, v67
	v_cvt_pk_bf16_f32 v67, v72, v73
	global_store_dwordx4 v[84:85], v[64:67], off offset:2048
	s_nop 1
	v_mul_f32_e32 v66, 0xbfb8aa3b, v173
	v_pk_mul_f32 v[70:71], v[62:63], v[66:67] op_sel_hi:[1,0]
	v_pk_mul_f32 v[72:73], v[60:61], v[66:67] op_sel_hi:[1,0]
	v_pk_mul_f32 v[74:75], v[58:59], v[66:67] op_sel_hi:[1,0]
	v_pk_mul_f32 v[66:67], v[56:57], v[66:67] op_sel_hi:[1,0]
	v_exp_f32_e32 v70, v70
	v_exp_f32_e32 v71, v71
	v_exp_f32_e32 v72, v72
	v_exp_f32_e32 v73, v73
	v_exp_f32_e32 v66, v66
	v_exp_f32_e32 v74, v74
	v_exp_f32_e32 v75, v75
	v_exp_f32_e32 v67, v67
	v_pk_fma_f32 v[70:71], v[70:71], v[236:237], v[236:237]
	v_pk_fma_f32 v[72:73], v[72:73], v[236:237], v[236:237]
	v_pk_fma_f32 v[74:75], v[74:75], v[236:237], v[236:237]
	v_pk_fma_f32 v[66:67], v[66:67], v[236:237], v[236:237]
	v_rcp_f32_e32 v70, v70
	v_rcp_f32_e32 v71, v71
	v_rcp_f32_e32 v72, v72
	v_rcp_f32_e32 v73, v73
	v_rcp_f32_e32 v66, v66
	v_rcp_f32_e32 v67, v67
	v_rcp_f32_e32 v74, v74
	v_rcp_f32_e32 v75, v75
	v_lshrrev_b32_e32 v64, 8, v150
	v_mad_i32_i24 v64, v64, 44, s11
	v_ashrrev_i32_e32 v65, 31, v64
	s_nop 0
	v_pk_mul_f32 v[54:55], v[54:55], v[70:71]
	v_lshlrev_b64 v[64:65], 15, v[64:65]
	v_pk_mul_f32 v[52:53], v[52:53], v[72:73]
; #define PG8_BAR __builtin_amdgcn_s_barrier()
;     __device__ __forceinline__ void operator()(const f32x4 (&acc)[2][2][4][2], const Unit& u, int wr, int wc, int fr, int fq) const {
;     ...
;                 const int row = row0 + ai * HALF + m * 16; const float rs = rsv[ai][m], cexp = -1.4426950408889634f * rs, rs2 = rs * rs;
;                 const f32x4 g0 = acc[ai][0][m][0], g1 = acc[ai][0][m][1], u0 = acc[ai][1][m][0], u1 = acc[ai][1][m][1];
;                 const f32x4 t0 = g0 * cexp, t1 = g1 * cexp;
;                 f32x4 d0 = (f32x4){__builtin_amdgcn_exp2f(t0[0]), __builtin_amdgcn_exp2f(t0[1]), __builtin_amdgcn_exp2f(t0[2]), __builtin_amdgcn_exp2f(t0[3])} + 1.0f;
;                 f32x4 d1 = (f32x4){__builtin_amdgcn_exp2f(t1[0]), __builtin_amdgcn_exp2f(t1[1]), __builtin_amdgcn_exp2f(t1[2]), __builtin_amdgcn_exp2f(t1[3])} + 1.0f;
;                 const f32x4 r0 = (f32x4){__builtin_amdgcn_rcpf(d0[0]), __builtin_amdgcn_rcpf(d0[1]), __builtin_amdgcn_rcpf(d0[2]), __builtin_amdgcn_rcpf(d0[3])} * rs2;
;                 const f32x4 r1 = (f32x4){__builtin_amdgcn_rcpf(d1[0]), __builtin_amdgcn_rcpf(d1[1]), __builtin_amdgcn_rcpf(d1[2]), __builtin_amdgcn_rcpf(d1[3])} * rs2;
;                 const f32x4 a0 = (g0 * u0) * r0, a1 = (g1 * u1) * r1;
;                 u32x4 w; w.x = cvt_pk_bf16(a0[0], a0[1]); w.y = cvt_pk_bf16(a0[2], a0[3]); w.z = cvt_pk_bf16(a1[0], a1[1]); w.w = cvt_pk_bf16(a1[2], a1[3]);
;                 *(u32x4*)(O + (((size_t)(row >> 8) * (DFF / BK) + (col0 >> 6)) * BM + (row & 255)) * BK + (col0 & 63)) = w;
; template <class Epi, class Sched, bool ALIGN_EPI = false, bool SP2 = false, bool ATILED = false>
; __device__ __forceinline__ void gemm_phase(PG8_LAS unsigned char* lds, const Gemm g, const Sched& S, const Epi& E) {
;     ...
;         if constexpr (!Epi::AFTER_DRAIN) { E(acc, cur, wr, wc, fr, fq); S.done(cur); }
;         if (!has_next) break;
; #pragma unroll
;         for (int a = 0; a < 2; ++a)
; #pragma unroll
;             for (int b = 0; b < 2; ++b)
; #pragma unroll
;                 for (int m = 0; m < 4; ++m)
; #pragma unroll
;                     for (int n = 0; n < 2; ++n) acc[a][b][m][n] = (f32x4){0.f, 0.f, 0.f, 0.f};
;         cur = nxt; cA = nA; cB = nB; ++ui;
;         if constexpr (ALIGN_EPI) { if (wr == 1) PG8_BAR; }
	v_pk_mul_f32 v[56:57], v[50:51], v[74:75]
	v_pk_mul_f32 v[50:51], v[48:49], v[66:67]
	v_cvt_pk_bf16_f32 v49, v54, v55
	v_lshlrev_b32_e32 v54, 7, v150
	v_cvt_pk_bf16_f32 v48, v52, v53
	v_lshl_add_u64 v[52:53], s[36:37], 0, v[64:65]
	v_and_b32_e32 v136, 0x6780, v54
	v_lshl_add_u64 v[52:53], v[52:53], 0, v[136:137]
	v_cvt_pk_bf16_f32 v50, v50, v51
	v_cvt_pk_bf16_f32 v51, v56, v57
	v_lshl_add_u64 v[52:53], v[52:53], 0, v[148:149]
	global_store_dwordx4 v[52:53], v[48:51], off
	s_nop 1
	v_mul_f32_e32 v48, 0xbfb8aa3b, v174
	v_pk_mul_f32 v[54:55], v[46:47], v[48:49] op_sel_hi:[1,0]
	v_pk_mul_f32 v[56:57], v[44:45], v[48:49] op_sel_hi:[1,0]
	v_pk_mul_f32 v[58:59], v[42:43], v[48:49] op_sel_hi:[1,0]
	v_pk_mul_f32 v[48:49], v[40:41], v[48:49] op_sel_hi:[1,0]
	v_exp_f32_e32 v56, v56
	v_exp_f32_e32 v57, v57
	v_exp_f32_e32 v54, v54
	v_exp_f32_e32 v55, v55
	v_exp_f32_e32 v48, v48
	v_exp_f32_e32 v58, v58
	v_exp_f32_e32 v59, v59
	v_exp_f32_e32 v49, v49
	v_pk_fma_f32 v[54:55], v[54:55], v[242:243], v[242:243]
	v_pk_fma_f32 v[56:57], v[56:57], v[242:243], v[242:243]
	v_pk_fma_f32 v[58:59], v[58:59], v[242:243], v[242:243]
	v_pk_fma_f32 v[48:49], v[48:49], v[242:243], v[242:243]
	v_rcp_f32_e32 v56, v56
	v_rcp_f32_e32 v57, v57
	v_rcp_f32_e32 v54, v54
	v_rcp_f32_e32 v55, v55
	v_rcp_f32_e32 v48, v48
	v_rcp_f32_e32 v49, v49
	v_rcp_f32_e32 v58, v58
	v_rcp_f32_e32 v59, v59
	s_nop 0
	v_pk_mul_f32 v[38:39], v[38:39], v[54:55]
	v_pk_mul_f32 v[36:37], v[36:37], v[56:57]
	v_pk_mul_f32 v[40:41], v[34:35], v[58:59]
	v_pk_mul_f32 v[34:35], v[32:33], v[48:49]
	v_cvt_pk_bf16_f32 v32, v36, v37
	v_cvt_pk_bf16_f32 v33, v38, v39
	v_cvt_pk_bf16_f32 v34, v34, v35
	v_cvt_pk_bf16_f32 v35, v40, v41
	global_store_dwordx4 v[52:53], v[32:35], off offset:2048
	s_nop 1
	v_mul_f32_e32 v32, 0xbfb8aa3b, v175
	v_pk_mul_f32 v[38:39], v[28:29], v[32:33] op_sel_hi:[1,0]
	v_pk_mul_f32 v[36:37], v[30:31], v[32:33] op_sel_hi:[1,0]
	v_pk_mul_f32 v[40:41], v[26:27], v[32:33] op_sel_hi:[1,0]
	v_pk_mul_f32 v[32:33], v[24:25], v[32:33] op_sel_hi:[1,0]
	v_exp_f32_e32 v38, v38
	v_exp_f32_e32 v39, v39
	v_exp_f32_e32 v36, v36
	v_exp_f32_e32 v37, v37
	v_exp_f32_e32 v32, v32
	v_exp_f32_e32 v40, v40
	v_exp_f32_e32 v41, v41
	v_exp_f32_e32 v33, v33
	v_pk_fma_f32 v[38:39], v[38:39], v[244:245], v[244:245]
	v_pk_fma_f32 v[36:37], v[36:37], v[244:245], v[244:245]
	v_pk_fma_f32 v[40:41], v[40:41], v[244:245], v[244:245]
	v_pk_fma_f32 v[32:33], v[32:33], v[244:245], v[244:245]
	v_rcp_f32_e32 v38, v38
	v_rcp_f32_e32 v39, v39
	v_rcp_f32_e32 v36, v36
	v_rcp_f32_e32 v37, v37
	v_rcp_f32_e32 v32, v32
	v_rcp_f32_e32 v33, v33
	v_rcp_f32_e32 v40, v40
	v_rcp_f32_e32 v41, v41
	s_nop 0
	v_pk_mul_f32 v[20:21], v[20:21], v[38:39]
	v_pk_mul_f32 v[22:23], v[22:23], v[36:37]
	v_pk_mul_f32 v[24:25], v[18:19], v[40:41]
	v_pk_mul_f32 v[18:19], v[16:17], v[32:33]
	v_cvt_pk_bf16_f32 v16, v20, v21
	v_add_co_u32_e32 v20, vcc, s62, v52
	v_cvt_pk_bf16_f32 v17, v22, v23
	v_cvt_pk_bf16_f32 v18, v18, v19
	v_cvt_pk_bf16_f32 v19, v24, v25
	v_addc_co_u32_e32 v21, vcc, 0, v53, vcc
	global_store_dwordx4 v[20:21], v[16:19], off
	s_andn2_b64 vcc, exec, s[0:1]
	s_mov_b64 s[0:1], -1
	v_mul_f32_e32 v16, 0xbfb8aa3b, v151
	v_pk_mul_f32 v[22:23], v[14:15], v[16:17] op_sel_hi:[1,0]
	v_pk_mul_f32 v[24:25], v[12:13], v[16:17] op_sel_hi:[1,0]
	v_pk_mul_f32 v[26:27], v[10:11], v[16:17] op_sel_hi:[1,0]
	v_pk_mul_f32 v[16:17], v[8:9], v[16:17] op_sel_hi:[1,0]
	v_exp_f32_e32 v24, v24
	v_exp_f32_e32 v25, v25
	v_exp_f32_e32 v22, v22
	v_exp_f32_e32 v23, v23
	v_exp_f32_e32 v16, v16
	v_exp_f32_e32 v26, v26
	v_exp_f32_e32 v27, v27
	v_exp_f32_e32 v17, v17
	v_pk_fma_f32 v[22:23], v[22:23], v[246:247], v[246:247]
	v_pk_fma_f32 v[24:25], v[24:25], v[246:247], v[246:247]
	v_pk_fma_f32 v[26:27], v[26:27], v[246:247], v[246:247]
	v_pk_fma_f32 v[16:17], v[16:17], v[246:247], v[246:247]
	v_rcp_f32_e32 v24, v24
	v_rcp_f32_e32 v25, v25
	v_rcp_f32_e32 v22, v22
	v_rcp_f32_e32 v23, v23
	v_rcp_f32_e32 v16, v16
	v_rcp_f32_e32 v17, v17
	v_rcp_f32_e32 v26, v26
	v_rcp_f32_e32 v27, v27
	s_nop 0
	v_pk_mul_f32 v[6:7], v[6:7], v[22:23]
	v_pk_mul_f32 v[4:5], v[4:5], v[24:25]
	v_pk_mul_f32 v[8:9], v[2:3], v[26:27]
	v_pk_mul_f32 v[2:3], v[0:1], v[16:17]
	v_cvt_pk_bf16_f32 v0, v4, v5
	v_cvt_pk_bf16_f32 v1, v6, v7
	v_cvt_pk_bf16_f32 v2, v2, v3
	v_cvt_pk_bf16_f32 v3, v8, v9
	global_store_dwordx4 v[20:21], v[0:3], off offset:2048
	s_cbranch_vccnz .LBB0_813
	s_andn2_b64 vcc, exec, s[4:5]
	s_cbranch_vccnz .LBB0_812
	s_barrier
	s_branch .LBB0_812
